# both dealt prompt-attention key loops placed at 0 mod 8 bytes (baseline had the majority copy at 0)
# baseline (speedup 1.0000x reference)
.LBB0_1975:
	s_nop 10
	v_exp_f32_e32 v67, v98
	v_exp_f32_e32 v68, v99
	v_exp_f32_e32 v69, v100
	v_exp_f32_e32 v70, v101
	v_exp_f32_e32 v71, v102
	v_exp_f32_e32 v72, v103
	v_exp_f32_e32 v73, v104
	v_exp_f32_e32 v74, v105
	v_add_f32_e32 v67, 1.0, v67
	v_add_f32_e32 v68, 1.0, v68
	v_add_f32_e32 v69, 1.0, v69
	v_add_f32_e32 v70, 1.0, v70
	v_add_f32_e32 v71, 1.0, v71
	v_add_f32_e32 v72, 1.0, v72
	v_add_f32_e32 v73, 1.0, v73
	v_add_f32_e32 v74, 1.0, v74
	v_log_f32_e32 v67, v67
	v_log_f32_e32 v68, v68
	v_log_f32_e32 v69, v69
	v_log_f32_e32 v70, v70
	v_log_f32_e32 v71, v71
	v_log_f32_e32 v72, v72
	v_log_f32_e32 v73, v73
	v_log_f32_e32 v74, v74
	v_exp_f32_e32 v75, v106
	v_exp_f32_e32 v76, v107
	v_exp_f32_e32 v77, v108
	v_exp_f32_e32 v78, v109
	v_exp_f32_e32 v79, v110
	v_exp_f32_e32 v80, v111
	v_exp_f32_e32 v81, v112
	v_exp_f32_e32 v179, v113
	v_cvt_pk_bf16_f32 v68, v67, v68
	v_cvt_pk_bf16_f32 v69, v69, v70
	v_cvt_pk_bf16_f32 v70, v71, v72
	v_cvt_pk_bf16_f32 v71, v73, v74
	v_mov_b32_e32 v83, v82
	v_mov_b32_e32 v84, v82
	v_mov_b32_e32 v85, v82
	v_mov_b32_e32 v86, v82
	v_mov_b32_e32 v87, v82
	v_mov_b32_e32 v88, v82
	v_mov_b32_e32 v89, v82
	v_mov_b32_e32 v90, v82
	v_mov_b32_e32 v91, v82
	v_mov_b32_e32 v92, v82
	v_mov_b32_e32 v93, v82
	v_mov_b32_e32 v94, v82
	v_mov_b32_e32 v95, v82
	v_mov_b32_e32 v96, v82
	v_mov_b32_e32 v97, v82
	v_add_f32_e32 v75, 1.0, v75
	v_add_f32_e32 v76, 1.0, v76
	v_mfma_f32_32x32x16_bf16 v[82:97], v[152:155], v[68:71], v[82:97]
	v_add_f32_e32 v77, 1.0, v77
	v_add_f32_e32 v78, 1.0, v78
	v_add_f32_e32 v79, 1.0, v79
	v_add_f32_e32 v80, 1.0, v80
	v_add_f32_e32 v81, 1.0, v81
	v_add_f32_e32 v68, 1.0, v179
	v_log_f32_e32 v75, v75
	v_log_f32_e32 v76, v76
	v_log_f32_e32 v77, v77
	v_log_f32_e32 v78, v78
	v_log_f32_e32 v79, v79
	v_log_f32_e32 v80, v80
	v_log_f32_e32 v67, v81
	v_log_f32_e32 v71, v68
	v_cvt_pk_bf16_f32 v68, v75, v76
	v_cvt_pk_bf16_f32 v69, v77, v78
	v_cvt_pk_bf16_f32 v70, v79, v80
	v_cvt_pk_bf16_f32 v71, v67, v71
	s_andn2_b64 vcc, exec, s[72:73]
	s_nop 0
	v_mfma_f32_32x32x16_bf16 v[82:97], v[148:151], v[68:71], v[82:97]
	s_nop 11
	v_sub_f32_e32 v68, v99, v83
	v_exp_f32_e32 v72, v68
	v_sub_f32_e32 v68, v100, v84
	v_exp_f32_e32 v73, v68
	v_sub_f32_e32 v68, v101, v85
	v_exp_f32_e32 v74, v68
	v_sub_f32_e32 v68, v102, v86
	v_exp_f32_e32 v75, v68
	v_sub_f32_e32 v68, v103, v87
	v_exp_f32_e32 v76, v68
	v_sub_f32_e32 v68, v104, v88
	v_exp_f32_e32 v77, v68
	v_sub_f32_e32 v68, v105, v89
	v_exp_f32_e32 v78, v68
	v_sub_f32_e32 v68, v106, v90
	v_exp_f32_e32 v80, v68
	v_sub_f32_e32 v68, v107, v91
	v_exp_f32_e32 v81, v68
	v_sub_f32_e32 v68, v108, v92
	v_exp_f32_e32 v83, v68
	v_sub_f32_e32 v68, v109, v93
	v_exp_f32_e32 v88, v68
	v_sub_f32_e32 v68, v110, v94
	v_exp_f32_e32 v89, v68
	v_sub_f32_e32 v68, v111, v95
	v_exp_f32_e32 v90, v68
	v_sub_f32_e32 v68, v112, v96
	v_exp_f32_e32 v91, v68
	v_xor_b32_e32 v68, v167, v174
	v_lshl_add_u32 v92, v68, 4, v177
	ds_read_b128 v[68:71], v92 offset:16384
	v_sub_f32_e32 v67, v98, v82
	v_exp_f32_e32 v67, v67
	v_cvt_pk_bf16_f32 v73, v73, v74
	v_cvt_pk_bf16_f32 v74, v75, v76
	v_cvt_pk_bf16_f32 v75, v77, v78
	v_cvt_pk_bf16_f32 v72, v67, v72
	v_xor_b32_e32 v67, v178, v167
	v_lshl_add_u32 v67, v67, 4, v177
	s_waitcnt lgkmcnt(0)
	v_mfma_f32_32x32x16_bf16 v[50:65], v[68:71], v[72:75], v[50:65]
	v_sub_f32_e32 v68, v113, v97
	ds_read_b128 v[76:79], v67 offset:16384
	ds_read_b128 v[84:87], v92 offset:20480
	v_exp_f32_e32 v71, v68
	v_cvt_pk_bf16_f32 v68, v80, v81
	v_cvt_pk_bf16_f32 v69, v83, v88
	v_cvt_pk_bf16_f32 v70, v89, v90
	v_cvt_pk_bf16_f32 v71, v91, v71
	ds_read_b128 v[88:91], v67 offset:20480
	s_waitcnt lgkmcnt(1)
	v_mfma_f32_32x32x16_bf16 v[34:49], v[84:87], v[72:75], v[34:49]
	v_mfma_f32_32x32x16_bf16 v[50:65], v[76:79], v[68:71], v[50:65]
	ds_read_b128 v[76:79], v92 offset:24576
	ds_read_b128 v[84:87], v92 offset:28672
	s_waitcnt lgkmcnt(1)
	v_mfma_f32_32x32x16_bf16 v[18:33], v[76:79], v[72:75], v[18:33]
	s_waitcnt lgkmcnt(0)
	v_mfma_f32_32x32x16_bf16 v[2:17], v[84:87], v[72:75], v[2:17]
	v_mfma_f32_32x32x16_bf16 v[34:49], v[88:91], v[68:71], v[34:49]
	ds_read_b128 v[76:79], v67 offset:24576
	ds_read_b128 v[88:91], v67 offset:28672
	v_and_or_b32 v67, v223, 64, v175
	v_lshlrev_b32_e32 v177, 2, v67
	ds_bpermute_b32 v67, v177, v82
	s_waitcnt lgkmcnt(2)
	v_mfma_f32_32x32x16_bf16 v[18:33], v[76:79], v[68:71], v[18:33]
	s_waitcnt lgkmcnt(1)
	v_mfma_f32_32x32x16_bf16 v[2:17], v[88:91], v[68:71], v[2:17]
	s_cbranch_vccnz .LBB0_1958
	s_sub_i32 s40, 0x7e, s46
	s_lshl_b32 s41, s40, 15
	v_bitop3_b32 v68, v174, v176, 1 bitop3:0x78
	s_and_b32 s41, s41, 0x18000
	v_lshl_add_u32 v176, v68, 4, v115
	s_add_i32 s41, s41, 0
	v_add_u32_e32 v93, s41, v176
	v_lshlrev_b32_e32 v178, 5, v167
	v_add_u32_e32 v68, v93, v178
	ds_read_b128 v[68:71], v68 offset:8192
	v_xor_b32_e32 v179, 32, v178
	v_add_u32_e32 v72, v93, v179
	ds_read_b128 v[84:87], v72 offset:8192
	v_xor_b32_e32 v180, 64, v178
	v_add_u32_e32 v88, v93, v180
	s_waitcnt lgkmcnt(1)
	v_mfma_f32_32x32x16_bf16 v[68:83], v[68:71], v[116:119], 0
	ds_read_b128 v[88:91], v88 offset:8192
	v_xor_b32_e32 v181, 0x60, v178
	v_xor_b32_e32 v182, 0x80, v178
	v_xor_b32_e32 v183, 0xa0, v178
	v_xor_b32_e32 v186, 0xc0, v178
	v_sub_f32_e32 v92, v67, v66
	v_lshrrev_b32_e32 v67, 1, v175
	s_waitcnt lgkmcnt(1)
	v_mfma_f32_32x32x16_bf16 v[68:83], v[84:87], v[120:123], v[68:83]
	v_add_u32_e32 v84, v93, v181
	ds_read_b128 v[84:87], v84 offset:8192
	v_xor_b32_e32 v187, 0xe0, v178
	v_bitop3_b32 v110, v67, v174, 1 bitop3:0x6c
	v_add_u32_e32 v67, v93, v187
	v_exp_f32_e32 v184, v66
	v_cndmask_b32_e64 v94, v171, 0, s[8:9]
	s_waitcnt lgkmcnt(1)
	v_mfma_f32_32x32x16_bf16 v[68:83], v[88:91], v[124:127], v[68:83]
	v_add_u32_e32 v88, v93, v182
	ds_read_b128 v[88:91], v88 offset:8192
	v_cndmask_b32_e64 v95, v171, 0, s[14:15]
	v_cndmask_b32_e64 v96, v171, 0, s[6:7]
	v_cndmask_b32_e64 v97, v171, 0, s[10:11]
	v_cndmask_b32_e64 v98, v171, 0, s[16:17]
	v_cndmask_b32_e64 v99, v171, 0, s[22:23]
	s_waitcnt lgkmcnt(1)
	v_mfma_f32_32x32x16_bf16 v[68:83], v[84:87], v[128:131], v[68:83]
	v_add_u32_e32 v84, v93, v183
	ds_read_b128 v[84:87], v84 offset:8192
	v_cndmask_b32_e64 v100, v171, 0, s[12:13]
	v_cndmask_b32_e64 v101, v171, 0, s[18:19]
	v_cndmask_b32_e64 v102, v171, 0, s[24:25]
	v_cndmask_b32_e64 v103, v171, 0, s[30:31]
	v_cndmask_b32_e64 v104, v171, 0, s[20:21]
	s_waitcnt lgkmcnt(1)
	v_mfma_f32_32x32x16_bf16 v[68:83], v[88:91], v[132:135], v[68:83]
	v_add_u32_e32 v88, v93, v186
	ds_read_b128 v[88:91], v88 offset:8192
	v_cndmask_b32_e64 v105, v171, 0, s[26:27]
	v_cndmask_b32_e64 v106, v171, 0, s[34:35]
	v_cndmask_b32_e64 v107, v171, 0, s[38:39]
	v_cndmask_b32_e64 v108, v171, 0, s[28:29]
	v_cndmask_b32_e64 v109, v171, 0, s[36:37]
	s_waitcnt lgkmcnt(1)
	v_mfma_f32_32x32x16_bf16 v[68:83], v[84:87], v[136:139], v[68:83]
	ds_read_b128 v[84:87], v67 offset:8192
	v_lshlrev_b32_e32 v66, 3, v175
	v_mov_b32_e32 v115, v157
	v_mov_b32_e32 v167, v157
	v_lshl_add_u32 v190, v110, 4, v163
	s_lshl_b32 s6, s46, 15
	s_lshl_b32 s7, s46, 6
	s_waitcnt lgkmcnt(1)
	v_mfma_f32_32x32x16_bf16 v[68:83], v[88:91], v[140:143], v[68:83]
	v_and_b32_e32 v185, 0x60, v66
	v_bitop3_b32 v174, v66, 32, v172 bitop3:0x6c
	v_bitop3_b32 v188, v66, 64, v172 bitop3:0x6c
	v_bitop3_b32 v189, v66, s76, v66 bitop3:0xc
	v_lshl_add_u64 v[66:67], s[60:61], 0, v[114:115]
	v_lshl_add_u64 v[166:167], s[60:61], 0, v[166:167]
	v_perm_b32 v151, v101, v100, s75
	s_waitcnt lgkmcnt(0)
	v_mfma_f32_32x32x16_bf16 v[68:83], v[84:87], v[144:147], v[68:83]
	v_mov_b32_e32 v84, 0
	v_perm_b32 v150, v99, v98, s75
	v_add_u32_e32 v175, 0, v190
	v_perm_b32 v149, v97, v96, s75
	v_perm_b32 v148, v95, v94, s75
	v_perm_b32 v155, v109, v108, s75
	v_perm_b32 v154, v107, v106, s75
	v_perm_b32 v153, v105, v104, s75
	v_perm_b32 v152, v103, v102, s75
	v_add_u32_e32 v191, 0, v176
	s_sub_i32 s6, 0x3e0000, s6
	s_sub_i32 s7, 0, s7
	v_mov_b32_e32 v85, v84
	v_mov_b32_e32 v86, v84
	v_mov_b32_e32 v87, v84
	v_mov_b32_e32 v88, v84
	v_mov_b32_e32 v89, v84
	v_mov_b32_e32 v90, v84
	v_mov_b32_e32 v91, v84
	s_branch .LBB0_1978
	.p2align 3
